# as best + D loops: both wave halves issue their 3 DMA pieces between their last 4 dependent P.V MFMAs
# speedup vs baseline: 1.0091x; 1.0089x over previous
; #define SBAR() __builtin_amdgcn_sched_barrier(0)
; template <int D0> __device__ __forceinline__ void pv_one(f32x16& od, int vb, bf16x8 pa0, bf16x8 pa1, bf16x8 pa2, bf16x8 pa3) {
;     const s16x4 l0 = tr_read<v_rd_off(D0, 0, 0)>(vb), h0 = tr_read<v_rd_off(D0, 0, 1)>(vb), l1 = tr_read<v_rd_off(D0, 1, 0)>(vb), h1 = tr_read<v_rd_off(D0, 1, 1)>(vb);
;     const s16x4 l2 = tr_read<v_rd_off(D0, 2, 0)>(vb), h2 = tr_read<v_rd_off(D0, 2, 1)>(vb), l3 = tr_read<v_rd_off(D0, 3, 0)>(vb), h3 = tr_read<v_rd_off(D0, 3, 1)>(vb);
;     asm volatile("s_waitcnt lgkmcnt(0)" ::: "memory"); SBAR();
;     ...
;     od = __builtin_amdgcn_mfma_f32_32x32x16_bf16(pa0, PK(l0, h0), od, 0, 0, 0);
;     od = __builtin_amdgcn_mfma_f32_32x32x16_bf16(pa1, PK(l1, h1), od, 0, 0, 0);
;     od = __builtin_amdgcn_mfma_f32_32x32x16_bf16(pa2, PK(l2, h2), od, 0, 0, 0);
;     od = __builtin_amdgcn_mfma_f32_32x32x16_bf16(pa3, PK(l3, h3), od, 0, 0, 0);
;     ...
; }
; template <bool RSM> __device__ __forceinline__ void pv_d0(f32x16* o, f32x16& lacc, int vb, bf16x8 pa0, bf16x8 pa1, bf16x8 pa2, bf16x8 pa3) {
;     if (RSM) {
;         const bf16x8 ones = {0x3F80, 0x3F80, 0x3F80, 0x3F80, 0x3F80, 0x3F80, 0x3F80, 0x3F80};
;         lacc = __builtin_amdgcn_mfma_f32_32x32x16_bf16(pa0, ones, lacc, 0, 0, 0);
;         lacc = __builtin_amdgcn_mfma_f32_32x32x16_bf16(pa1, ones, lacc, 0, 0, 0);
;         lacc = __builtin_amdgcn_mfma_f32_32x32x16_bf16(pa2, ones, lacc, 0, 0, 0);
;         lacc = __builtin_amdgcn_mfma_f32_32x32x16_bf16(pa3, ones, lacc, 0, 0, 0); }
;     pv_one<0>(o[0], vb, pa0, pa1, pa2, pa3); pv_one<1>(o[1], vb, pa0, pa1, pa2, pa3); pv_one<2>(o[2], vb, pa0, pa1, pa2, pa3); pv_one<3>(o[3], vb, pa0, pa1, pa2, pa3);
; template <int NQ, int MODE> ...
;     ...
;     bf16x8 qr[NQ];
;     const bf16_t* Qw = Qb + (long)(wid * QBLK + r32) * ldq + hi * 8;
;     __syncthreads();
; #pragma unroll
;     for (int d0 = 0; d0 < NQ; ++d0) qr[d0] = *reinterpret_cast<const bf16x8*>(Qw + d0 * 16);
;     DMA_K(0, 0); DMA_V(0, 0); DMA_K(1, 1);
;     const int lo1 = (hi ^ (r32 & 1)) << 4, s3 = (r32 >> 1) & 7, b1_ = r32 * 256 + lo1;
;     const int kb1[2] = {b1_, s3};
;     const int lo2 = (hi ^ ((r32 >> 1) & 1)) << 4, s2 = (r32 >> 2) & 3, b2_ = r32 * 128 + lo2;
;     const int kb2[2] = {b2_, s2};
;     const int vb0 = (int)(uintptr_t)V_lds + v_rd_base(lane);
;     const int kl0 = (int)(uintptr_t)K_lds;
;     const int qw = q0 + wid * QBLK;
.LBB0_704:
	s_mov_b32 s38, s36
	s_mov_b32 s39, s36
	s_mov_b32 s37, s36
	v_mov_b64_e32 v[134:135], s[38:39]
	v_mov_b64_e32 v[132:133], s[36:37]
	s_lshl_b32 s23, s35, 14
	v_add_u32_e32 v0, s23, v230
	v_mfma_f32_32x32x16_bf16 v[96:111], v[6:9], v[132:135], v[96:111]
	ds_read_b64_tr_b16 v[136:137], v0 offset:0
	ds_read_b64_tr_b16 v[138:139], v0 offset:0x800
	ds_read_b64_tr_b16 v[140:141], v0 offset:0x1000
	ds_read_b64_tr_b16 v[142:143], v0 offset:0x1800
	ds_read_b64_tr_b16 v[192:193], v0 offset:0x2000
	ds_read_b64_tr_b16 v[194:195], v0 offset:0x2800
	ds_read_b64_tr_b16 v[196:197], v0 offset:0x3000
	v_mfma_f32_32x32x16_bf16 v[96:111], v[2:5], v[132:135], v[96:111]
	ds_read_b64_tr_b16 v[198:199], v0 offset:0x3800
	s_waitcnt lgkmcnt(0)
	v_mfma_f32_32x32x16_bf16 v[96:111], v[128:131], v[132:135], v[96:111]
	v_mfma_f32_32x32x16_bf16 v[96:111], v[10:13], v[132:135], v[96:111]
	v_mfma_f32_32x32x16_bf16 v[80:95], v[6:9], v[136:139], v[80:95]
	ds_read_b64_tr_b16 v[132:133], v0 offset:0x200
	ds_read_b64_tr_b16 v[134:135], v0 offset:0xa00
	ds_read_b64_tr_b16 v[136:137], v0 offset:0x1200
	ds_read_b64_tr_b16 v[138:139], v0 offset:0x1a00
	v_mfma_f32_32x32x16_bf16 v[80:95], v[2:5], v[140:143], v[80:95]
	ds_read_b64_tr_b16 v[140:141], v0 offset:0x2200
	ds_read_b64_tr_b16 v[142:143], v0 offset:0x2a00
	v_mfma_f32_32x32x16_bf16 v[80:95], v[128:131], v[192:195], v[80:95]
	ds_read_b64_tr_b16 v[192:193], v0 offset:0x3200
	ds_read_b64_tr_b16 v[194:195], v0 offset:0x3a00
	s_waitcnt lgkmcnt(0)
	v_mfma_f32_32x32x16_bf16 v[80:95], v[10:13], v[196:199], v[80:95]
	v_mfma_f32_32x32x16_bf16 v[64:79], v[6:9], v[132:135], v[64:79]
	ds_read_b64_tr_b16 v[132:133], v0 offset:0x400
	ds_read_b64_tr_b16 v[134:135], v0 offset:0xc00
	v_mfma_f32_32x32x16_bf16 v[64:79], v[2:5], v[136:139], v[64:79]
	ds_read_b64_tr_b16 v[136:137], v0 offset:0x1400
	ds_read_b64_tr_b16 v[138:139], v0 offset:0x1c00
	v_mfma_f32_32x32x16_bf16 v[64:79], v[128:131], v[140:143], v[64:79]
	ds_read_b64_tr_b16 v[140:141], v0 offset:0x2400
	ds_read_b64_tr_b16 v[142:143], v0 offset:0x2c00
	v_mfma_f32_32x32x16_bf16 v[64:79], v[10:13], v[192:195], v[64:79]
	ds_read_b64_tr_b16 v[192:193], v0 offset:0x3400
	ds_read_b64_tr_b16 v[194:195], v0 offset:0x3c00
	s_waitcnt lgkmcnt(0)
	v_mfma_f32_32x32x16_bf16 v[48:63], v[6:9], v[132:135], v[48:63]
	ds_read_b64_tr_b16 v[132:133], v0 offset:0x600
	ds_read_b64_tr_b16 v[134:135], v0 offset:0xe00
	v_mfma_f32_32x32x16_bf16 v[48:63], v[2:5], v[136:139], v[48:63]
	ds_read_b64_tr_b16 v[136:137], v0 offset:0x1600
	ds_read_b64_tr_b16 v[138:139], v0 offset:0x1e00
	v_mfma_f32_32x32x16_bf16 v[48:63], v[128:131], v[140:143], v[48:63]
	ds_read_b64_tr_b16 v[140:141], v0 offset:0x2600
	ds_read_b64_tr_b16 v[142:143], v0 offset:0x2e00
	v_mfma_f32_32x32x16_bf16 v[48:63], v[10:13], v[192:195], v[48:63]
	ds_read_b64_tr_b16 v[192:193], v0 offset:0x3600
	ds_read_b64_tr_b16 v[194:195], v0 offset:0x3e00
	s_waitcnt lgkmcnt(0)
	s_and_b64 vcc, exec, s[0:1]
	s_cbranch_vccnz .Lmy_slow_0
	s_cmpk_gt_u32 s57, 0xfc
	s_cbranch_scc1 .Lmy_slow_0
	s_mov_b64 s[20:21], -1
	s_add_i32 m0, s81, s22
	s_addk_i32 s23, 0xc000
	s_cmp_gt_i32 s35, 0
	s_cselect_b32 s20, s23, 0xc000
	s_waitcnt vmcnt(3) lgkmcnt(0)
	s_barrier
	v_mfma_f32_32x32x16_bf16 v[32:47], v[6:9], v[132:135], v[32:47]
	global_load_lds_dwordx4 v[214:215], off
	v_lshl_add_u64 v[214:215], v[214:215], 0, s[74:75]
	s_and_b64 vcc, exec, s[0:1]
	v_mfma_f32_32x32x16_bf16 v[32:47], v[2:5], v[136:139], v[32:47]
	s_add_i32 s20, s63, s20
	s_mov_b32 m0, s20
	s_nop 0
	global_load_lds_dwordx4 v[212:213], off
	v_mfma_f32_32x32x16_bf16 v[32:47], v[128:131], v[140:143], v[32:47]
	s_add_i32 m0, s20, 0x2000
	s_nop 0
	global_load_lds_dwordx4 v[216:217], off
	v_mfma_f32_32x32x16_bf16 v[32:47], v[10:13], v[192:195], v[32:47]
	v_lshl_add_u64 v[2:3], v[212:213], 0, s[74:75]
	v_lshl_add_u64 v[4:5], v[216:217], 0, s[74:75]
	v_mov_b64_e32 v[216:217], v[4:5]
	v_mov_b64_e32 v[212:213], v[2:3]
	s_branch .LBB0_709

; #define SBAR() __builtin_amdgcn_sched_barrier(0)
; template <int D0> __device__ __forceinline__ void pv_one(f32x16& od, int vb, bf16x8 pa0, bf16x8 pa1, bf16x8 pa2, bf16x8 pa3) {
;     const s16x4 l0 = tr_read<v_rd_off(D0, 0, 0)>(vb), h0 = tr_read<v_rd_off(D0, 0, 1)>(vb), l1 = tr_read<v_rd_off(D0, 1, 0)>(vb), h1 = tr_read<v_rd_off(D0, 1, 1)>(vb);
;     const s16x4 l2 = tr_read<v_rd_off(D0, 2, 0)>(vb), h2 = tr_read<v_rd_off(D0, 2, 1)>(vb), l3 = tr_read<v_rd_off(D0, 3, 0)>(vb), h3 = tr_read<v_rd_off(D0, 3, 1)>(vb);
;     asm volatile("s_waitcnt lgkmcnt(0)" ::: "memory"); SBAR();
;     ...
;     od = __builtin_amdgcn_mfma_f32_32x32x16_bf16(pa0, PK(l0, h0), od, 0, 0, 0);
;     od = __builtin_amdgcn_mfma_f32_32x32x16_bf16(pa1, PK(l1, h1), od, 0, 0, 0);
;     od = __builtin_amdgcn_mfma_f32_32x32x16_bf16(pa2, PK(l2, h2), od, 0, 0, 0);
;     od = __builtin_amdgcn_mfma_f32_32x32x16_bf16(pa3, PK(l3, h3), od, 0, 0, 0);
;     ...
; }
; template <bool RSM> __device__ __forceinline__ void pv_d0(f32x16* o, f32x16& lacc, int vb, bf16x8 pa0, bf16x8 pa1, bf16x8 pa2, bf16x8 pa3) {
;     if (RSM) {
;         const bf16x8 ones = {0x3F80, 0x3F80, 0x3F80, 0x3F80, 0x3F80, 0x3F80, 0x3F80, 0x3F80};
;         lacc = __builtin_amdgcn_mfma_f32_32x32x16_bf16(pa0, ones, lacc, 0, 0, 0);
;         lacc = __builtin_amdgcn_mfma_f32_32x32x16_bf16(pa1, ones, lacc, 0, 0, 0);
;         lacc = __builtin_amdgcn_mfma_f32_32x32x16_bf16(pa2, ones, lacc, 0, 0, 0);
;         lacc = __builtin_amdgcn_mfma_f32_32x32x16_bf16(pa3, ones, lacc, 0, 0, 0); }
;     pv_one<0>(o[0], vb, pa0, pa1, pa2, pa3); pv_one<1>(o[1], vb, pa0, pa1, pa2, pa3); pv_one<2>(o[2], vb, pa0, pa1, pa2, pa3); pv_one<3>(o[3], vb, pa0, pa1, pa2, pa3);
; template <int NQ, int MODE> ...
;     ...
;     bf16x8 qr[NQ];
;     const bf16_t* Qw = Qb + (long)(wid * QBLK + r32) * ldq + hi * 8;
;     __syncthreads();
; #pragma unroll
;     for (int d0 = 0; d0 < NQ; ++d0) qr[d0] = *reinterpret_cast<const bf16x8*>(Qw + d0 * 16);
;     DMA_K(0, 0); DMA_V(0, 0); DMA_K(1, 1);
;     const int lo1 = (hi ^ (r32 & 1)) << 4, s3 = (r32 >> 1) & 7, b1_ = r32 * 256 + lo1;
;     const int kb1[2] = {b1_, s3};
;     const int lo2 = (hi ^ ((r32 >> 1) & 1)) << 4, s2 = (r32 >> 2) & 3, b2_ = r32 * 128 + lo2;
;     const int kb2[2] = {b2_, s2};
;     const int vb0 = (int)(uintptr_t)V_lds + v_rd_base(lane);
;     const int kl0 = (int)(uintptr_t)K_lds;
;     const int qw = q0 + wid * QBLK;
.LBB0_719:
	s_mov_b32 s38, s36
	s_mov_b32 s39, s36
	s_mov_b32 s37, s36
	v_mov_b64_e32 v[150:151], s[38:39]
	v_mov_b64_e32 v[148:149], s[36:37]
	s_lshl_b32 s37, s35, 14
	v_add_u32_e32 v14, s37, v230
	v_mfma_f32_32x32x16_bf16 v[96:111], v[6:9], v[148:151], v[96:111]
	ds_read_b64_tr_b16 v[152:153], v14 offset:0
	ds_read_b64_tr_b16 v[154:155], v14 offset:0x800
	ds_read_b64_tr_b16 v[156:157], v14 offset:0x1000
	ds_read_b64_tr_b16 v[158:159], v14 offset:0x1800
	ds_read_b64_tr_b16 v[192:193], v14 offset:0x2000
	ds_read_b64_tr_b16 v[194:195], v14 offset:0x2800
	ds_read_b64_tr_b16 v[196:197], v14 offset:0x3000
	v_mfma_f32_32x32x16_bf16 v[96:111], v[2:5], v[148:151], v[96:111]
	ds_read_b64_tr_b16 v[198:199], v14 offset:0x3800
	s_waitcnt lgkmcnt(0)
	v_mfma_f32_32x32x16_bf16 v[96:111], v[144:147], v[148:151], v[96:111]
	v_mfma_f32_32x32x16_bf16 v[96:111], v[10:13], v[148:151], v[96:111]
	v_mfma_f32_32x32x16_bf16 v[80:95], v[6:9], v[152:155], v[80:95]
	ds_read_b64_tr_b16 v[148:149], v14 offset:0x200
	ds_read_b64_tr_b16 v[150:151], v14 offset:0xa00
	ds_read_b64_tr_b16 v[152:153], v14 offset:0x1200
	ds_read_b64_tr_b16 v[154:155], v14 offset:0x1a00
	v_mfma_f32_32x32x16_bf16 v[80:95], v[2:5], v[156:159], v[80:95]
	ds_read_b64_tr_b16 v[156:157], v14 offset:0x2200
	ds_read_b64_tr_b16 v[158:159], v14 offset:0x2a00
	v_mfma_f32_32x32x16_bf16 v[80:95], v[144:147], v[192:195], v[80:95]
	ds_read_b64_tr_b16 v[192:193], v14 offset:0x3200
	ds_read_b64_tr_b16 v[194:195], v14 offset:0x3a00
	s_waitcnt lgkmcnt(0)
	v_mfma_f32_32x32x16_bf16 v[80:95], v[10:13], v[196:199], v[80:95]
	v_mfma_f32_32x32x16_bf16 v[64:79], v[6:9], v[148:151], v[64:79]
	ds_read_b64_tr_b16 v[148:149], v14 offset:0x400
	ds_read_b64_tr_b16 v[150:151], v14 offset:0xc00
	v_mfma_f32_32x32x16_bf16 v[64:79], v[2:5], v[152:155], v[64:79]
	ds_read_b64_tr_b16 v[152:153], v14 offset:0x1400
	ds_read_b64_tr_b16 v[154:155], v14 offset:0x1c00
	v_mfma_f32_32x32x16_bf16 v[64:79], v[144:147], v[156:159], v[64:79]
	ds_read_b64_tr_b16 v[156:157], v14 offset:0x2400
	ds_read_b64_tr_b16 v[158:159], v14 offset:0x2c00
	v_mfma_f32_32x32x16_bf16 v[64:79], v[10:13], v[192:195], v[64:79]
	ds_read_b64_tr_b16 v[192:193], v14 offset:0x3400
	ds_read_b64_tr_b16 v[194:195], v14 offset:0x3c00
	s_waitcnt lgkmcnt(0)
	v_mfma_f32_32x32x16_bf16 v[48:63], v[6:9], v[148:151], v[48:63]
	ds_read_b64_tr_b16 v[148:149], v14 offset:0x600
	ds_read_b64_tr_b16 v[150:151], v14 offset:0xe00
	v_mfma_f32_32x32x16_bf16 v[48:63], v[2:5], v[152:155], v[48:63]
	ds_read_b64_tr_b16 v[152:153], v14 offset:0x1600
	ds_read_b64_tr_b16 v[154:155], v14 offset:0x1e00
	v_mfma_f32_32x32x16_bf16 v[48:63], v[144:147], v[156:159], v[48:63]
	ds_read_b64_tr_b16 v[156:157], v14 offset:0x2600
	ds_read_b64_tr_b16 v[158:159], v14 offset:0x2e00
	v_mfma_f32_32x32x16_bf16 v[48:63], v[10:13], v[192:195], v[48:63]
	ds_read_b64_tr_b16 v[192:193], v14 offset:0x3600
	ds_read_b64_tr_b16 v[194:195], v14 offset:0x3e00
	s_waitcnt lgkmcnt(0)
	s_and_b64 vcc, exec, s[0:1]
	s_cbranch_vccnz .Lmy_slow_1
	s_cmpk_gt_u32 s57, 0xfb
	s_cbranch_scc1 .Lmy_slow_1
	s_mov_b64 s[22:23], -1
	s_add_i32 m0, s81, s78
	s_addk_i32 s37, 0xc000
	s_cmp_gt_i32 s35, 0
	s_cselect_b32 s22, s37, 0xc000
	s_waitcnt vmcnt(3) lgkmcnt(0)
	s_barrier
	v_mfma_f32_32x32x16_bf16 v[32:47], v[6:9], v[148:151], v[32:47]
	global_load_lds_dwordx4 v[214:215], off
	v_lshl_add_u64 v[214:215], v[214:215], 0, s[74:75]
	s_and_b64 vcc, exec, s[0:1]
	v_mfma_f32_32x32x16_bf16 v[32:47], v[2:5], v[152:155], v[32:47]
	s_add_i32 s22, s63, s22
	s_mov_b32 m0, s22
	s_nop 0
	global_load_lds_dwordx4 v[212:213], off
	v_mfma_f32_32x32x16_bf16 v[32:47], v[144:147], v[156:159], v[32:47]
	s_add_i32 m0, s22, 0x2000
	s_nop 0
	global_load_lds_dwordx4 v[216:217], off
	v_mfma_f32_32x32x16_bf16 v[32:47], v[10:13], v[192:195], v[32:47]
	v_lshl_add_u64 v[2:3], v[212:213], 0, s[74:75]
	v_lshl_add_u64 v[4:5], v[216:217], 0, s[74:75]
	v_mov_b64_e32 v[216:217], v[4:5]
	v_mov_b64_e32 v[212:213], v[2:3]
	s_branch .LBB0_724

; #define SBAR() __builtin_amdgcn_sched_barrier(0)
; template <int D0> __device__ __forceinline__ void pv_one(f32x16& od, int vb, bf16x8 pa0, bf16x8 pa1, bf16x8 pa2, bf16x8 pa3) {
;     const s16x4 l0 = tr_read<v_rd_off(D0, 0, 0)>(vb), h0 = tr_read<v_rd_off(D0, 0, 1)>(vb), l1 = tr_read<v_rd_off(D0, 1, 0)>(vb), h1 = tr_read<v_rd_off(D0, 1, 1)>(vb);
;     const s16x4 l2 = tr_read<v_rd_off(D0, 2, 0)>(vb), h2 = tr_read<v_rd_off(D0, 2, 1)>(vb), l3 = tr_read<v_rd_off(D0, 3, 0)>(vb), h3 = tr_read<v_rd_off(D0, 3, 1)>(vb);
;     asm volatile("s_waitcnt lgkmcnt(0)" ::: "memory"); SBAR();
;     ...
;     od = __builtin_amdgcn_mfma_f32_32x32x16_bf16(pa0, PK(l0, h0), od, 0, 0, 0);
;     od = __builtin_amdgcn_mfma_f32_32x32x16_bf16(pa1, PK(l1, h1), od, 0, 0, 0);
;     od = __builtin_amdgcn_mfma_f32_32x32x16_bf16(pa2, PK(l2, h2), od, 0, 0, 0);
;     od = __builtin_amdgcn_mfma_f32_32x32x16_bf16(pa3, PK(l3, h3), od, 0, 0, 0);
;     ...
; }
; template <bool RSM> __device__ __forceinline__ void pv_d0(f32x16* o, f32x16& lacc, int vb, bf16x8 pa0, bf16x8 pa1, bf16x8 pa2, bf16x8 pa3) {
;     if (RSM) {
;         const bf16x8 ones = {0x3F80, 0x3F80, 0x3F80, 0x3F80, 0x3F80, 0x3F80, 0x3F80, 0x3F80};
;         lacc = __builtin_amdgcn_mfma_f32_32x32x16_bf16(pa0, ones, lacc, 0, 0, 0);
;         lacc = __builtin_amdgcn_mfma_f32_32x32x16_bf16(pa1, ones, lacc, 0, 0, 0);
;         lacc = __builtin_amdgcn_mfma_f32_32x32x16_bf16(pa2, ones, lacc, 0, 0, 0);
;         lacc = __builtin_amdgcn_mfma_f32_32x32x16_bf16(pa3, ones, lacc, 0, 0, 0); }
;     pv_one<0>(o[0], vb, pa0, pa1, pa2, pa3); pv_one<1>(o[1], vb, pa0, pa1, pa2, pa3); pv_one<2>(o[2], vb, pa0, pa1, pa2, pa3); pv_one<3>(o[3], vb, pa0, pa1, pa2, pa3);
; template <int NQ, int MODE> ...
;     ...
;     bf16x8 qr[NQ];
;     const bf16_t* Qw = Qb + (long)(wid * QBLK + r32) * ldq + hi * 8;
;     __syncthreads();
; #pragma unroll
;     for (int d0 = 0; d0 < NQ; ++d0) qr[d0] = *reinterpret_cast<const bf16x8*>(Qw + d0 * 16);
;     DMA_K(0, 0); DMA_V(0, 0); DMA_K(1, 1);
;     const int lo1 = (hi ^ (r32 & 1)) << 4, s3 = (r32 >> 1) & 7, b1_ = r32 * 256 + lo1;
;     const int kb1[2] = {b1_, s3};
;     const int lo2 = (hi ^ ((r32 >> 1) & 1)) << 4, s2 = (r32 >> 2) & 3, b2_ = r32 * 128 + lo2;
;     const int kb2[2] = {b2_, s2};
;     const int vb0 = (int)(uintptr_t)V_lds + v_rd_base(lane);
;     const int kl0 = (int)(uintptr_t)K_lds;
;     const int qw = q0 + wid * QBLK;
.Lmy_r2d_0:
	s_mov_b32 s38, s36
	s_mov_b32 s39, s36
	s_mov_b32 s37, s36
	v_mov_b64_e32 v[134:135], s[38:39]
	v_mov_b64_e32 v[132:133], s[36:37]
	s_lshl_b32 s23, s35, 14
	v_add_u32_e32 v0, s23, v230
	v_mfma_f32_32x32x16_bf16 v[96:111], v[6:9], v[132:135], v[96:111]
	ds_read_b64_tr_b16 v[136:137], v0 offset:0
	ds_read_b64_tr_b16 v[138:139], v0 offset:0x800
	ds_read_b64_tr_b16 v[140:141], v0 offset:0x1000
	ds_read_b64_tr_b16 v[142:143], v0 offset:0x1800
	ds_read_b64_tr_b16 v[192:193], v0 offset:0x2000
	ds_read_b64_tr_b16 v[194:195], v0 offset:0x2800
	ds_read_b64_tr_b16 v[196:197], v0 offset:0x3000
	v_mfma_f32_32x32x16_bf16 v[96:111], v[2:5], v[132:135], v[96:111]
	ds_read_b64_tr_b16 v[198:199], v0 offset:0x3800
	s_waitcnt lgkmcnt(0)
	v_mfma_f32_32x32x16_bf16 v[96:111], v[128:131], v[132:135], v[96:111]
	v_mfma_f32_32x32x16_bf16 v[96:111], v[10:13], v[132:135], v[96:111]
	v_mfma_f32_32x32x16_bf16 v[80:95], v[6:9], v[136:139], v[80:95]
	ds_read_b64_tr_b16 v[132:133], v0 offset:0x200
	ds_read_b64_tr_b16 v[134:135], v0 offset:0xa00
	ds_read_b64_tr_b16 v[136:137], v0 offset:0x1200
	ds_read_b64_tr_b16 v[138:139], v0 offset:0x1a00
	v_mfma_f32_32x32x16_bf16 v[80:95], v[2:5], v[140:143], v[80:95]
	ds_read_b64_tr_b16 v[140:141], v0 offset:0x2200
	ds_read_b64_tr_b16 v[142:143], v0 offset:0x2a00
	v_mfma_f32_32x32x16_bf16 v[80:95], v[128:131], v[192:195], v[80:95]
	ds_read_b64_tr_b16 v[192:193], v0 offset:0x3200
	ds_read_b64_tr_b16 v[194:195], v0 offset:0x3a00
	s_waitcnt lgkmcnt(0)
	v_mfma_f32_32x32x16_bf16 v[80:95], v[10:13], v[196:199], v[80:95]
	v_mfma_f32_32x32x16_bf16 v[64:79], v[6:9], v[132:135], v[64:79]
	ds_read_b64_tr_b16 v[132:133], v0 offset:0x400
	ds_read_b64_tr_b16 v[134:135], v0 offset:0xc00
	v_mfma_f32_32x32x16_bf16 v[64:79], v[2:5], v[136:139], v[64:79]
	ds_read_b64_tr_b16 v[136:137], v0 offset:0x1400
	ds_read_b64_tr_b16 v[138:139], v0 offset:0x1c00
	v_mfma_f32_32x32x16_bf16 v[64:79], v[128:131], v[140:143], v[64:79]
	ds_read_b64_tr_b16 v[140:141], v0 offset:0x2400
	ds_read_b64_tr_b16 v[142:143], v0 offset:0x2c00
	v_mfma_f32_32x32x16_bf16 v[64:79], v[10:13], v[192:195], v[64:79]
	ds_read_b64_tr_b16 v[192:193], v0 offset:0x3400
	ds_read_b64_tr_b16 v[194:195], v0 offset:0x3c00
	s_waitcnt lgkmcnt(0)
	v_mfma_f32_32x32x16_bf16 v[48:63], v[6:9], v[132:135], v[48:63]
	ds_read_b64_tr_b16 v[132:133], v0 offset:0x600
	ds_read_b64_tr_b16 v[134:135], v0 offset:0xe00
	v_mfma_f32_32x32x16_bf16 v[48:63], v[2:5], v[136:139], v[48:63]
	ds_read_b64_tr_b16 v[136:137], v0 offset:0x1600
	ds_read_b64_tr_b16 v[138:139], v0 offset:0x1e00
	v_mfma_f32_32x32x16_bf16 v[48:63], v[128:131], v[140:143], v[48:63]
	ds_read_b64_tr_b16 v[140:141], v0 offset:0x2600
	ds_read_b64_tr_b16 v[142:143], v0 offset:0x2e00
	v_mfma_f32_32x32x16_bf16 v[48:63], v[10:13], v[192:195], v[48:63]
	ds_read_b64_tr_b16 v[192:193], v0 offset:0x3600
	ds_read_b64_tr_b16 v[194:195], v0 offset:0x3e00
	s_waitcnt lgkmcnt(0)
	v_mfma_f32_32x32x16_bf16 v[32:47], v[6:9], v[132:135], v[32:47]
	global_load_lds_dwordx4 v[214:215], off
	v_lshl_add_u64 v[214:215], v[214:215], 0, s[74:75]
	s_and_b64 vcc, exec, s[0:1]
	v_mfma_f32_32x32x16_bf16 v[32:47], v[2:5], v[136:139], v[32:47]
	s_mov_b32 m0, s20
	s_nop 0
	global_load_lds_dwordx4 v[212:213], off
	v_lshl_add_u64 v[212:213], v[212:213], 0, s[74:75]
	v_mfma_f32_32x32x16_bf16 v[32:47], v[128:131], v[140:143], v[32:47]
	s_add_i32 m0, s20, 0x2000
	s_nop 0
	global_load_lds_dwordx4 v[216:217], off
	v_lshl_add_u64 v[216:217], v[216:217], 0, s[74:75]
	v_mfma_f32_32x32x16_bf16 v[32:47], v[10:13], v[192:195], v[32:47]
	s_cbranch_vccnz .LBB0_709
	s_branch .Lmy_r2ft_0
.Lmy_r2d_1:
	s_mov_b32 s38, s36
	s_mov_b32 s39, s36
	s_mov_b32 s37, s36
	v_mov_b64_e32 v[150:151], s[38:39]
	v_mov_b64_e32 v[148:149], s[36:37]
	s_lshl_b32 s37, s35, 14
	v_add_u32_e32 v14, s37, v230
	v_mfma_f32_32x32x16_bf16 v[96:111], v[6:9], v[148:151], v[96:111]
	ds_read_b64_tr_b16 v[152:153], v14 offset:0
	ds_read_b64_tr_b16 v[154:155], v14 offset:0x800
	ds_read_b64_tr_b16 v[156:157], v14 offset:0x1000
	ds_read_b64_tr_b16 v[158:159], v14 offset:0x1800
	ds_read_b64_tr_b16 v[192:193], v14 offset:0x2000
	ds_read_b64_tr_b16 v[194:195], v14 offset:0x2800
	ds_read_b64_tr_b16 v[196:197], v14 offset:0x3000
	v_mfma_f32_32x32x16_bf16 v[96:111], v[2:5], v[148:151], v[96:111]
	ds_read_b64_tr_b16 v[198:199], v14 offset:0x3800
	s_waitcnt lgkmcnt(0)
	v_mfma_f32_32x32x16_bf16 v[96:111], v[144:147], v[148:151], v[96:111]
	v_mfma_f32_32x32x16_bf16 v[96:111], v[10:13], v[148:151], v[96:111]
	v_mfma_f32_32x32x16_bf16 v[80:95], v[6:9], v[152:155], v[80:95]
	ds_read_b64_tr_b16 v[148:149], v14 offset:0x200
	ds_read_b64_tr_b16 v[150:151], v14 offset:0xa00
	ds_read_b64_tr_b16 v[152:153], v14 offset:0x1200
	ds_read_b64_tr_b16 v[154:155], v14 offset:0x1a00
	v_mfma_f32_32x32x16_bf16 v[80:95], v[2:5], v[156:159], v[80:95]
	ds_read_b64_tr_b16 v[156:157], v14 offset:0x2200
	ds_read_b64_tr_b16 v[158:159], v14 offset:0x2a00
	v_mfma_f32_32x32x16_bf16 v[80:95], v[144:147], v[192:195], v[80:95]
	ds_read_b64_tr_b16 v[192:193], v14 offset:0x3200
	ds_read_b64_tr_b16 v[194:195], v14 offset:0x3a00
	s_waitcnt lgkmcnt(0)
	v_mfma_f32_32x32x16_bf16 v[80:95], v[10:13], v[196:199], v[80:95]
	v_mfma_f32_32x32x16_bf16 v[64:79], v[6:9], v[148:151], v[64:79]
	ds_read_b64_tr_b16 v[148:149], v14 offset:0x400
	ds_read_b64_tr_b16 v[150:151], v14 offset:0xc00
	v_mfma_f32_32x32x16_bf16 v[64:79], v[2:5], v[152:155], v[64:79]
	ds_read_b64_tr_b16 v[152:153], v14 offset:0x1400
	ds_read_b64_tr_b16 v[154:155], v14 offset:0x1c00
	v_mfma_f32_32x32x16_bf16 v[64:79], v[144:147], v[156:159], v[64:79]
	ds_read_b64_tr_b16 v[156:157], v14 offset:0x2400
	ds_read_b64_tr_b16 v[158:159], v14 offset:0x2c00
	v_mfma_f32_32x32x16_bf16 v[64:79], v[10:13], v[192:195], v[64:79]
	ds_read_b64_tr_b16 v[192:193], v14 offset:0x3400
	ds_read_b64_tr_b16 v[194:195], v14 offset:0x3c00
	s_waitcnt lgkmcnt(0)
; #define SBAR() __builtin_amdgcn_sched_barrier(0)
; template <int D0> __device__ __forceinline__ void pv_one(f32x16& od, int vb, bf16x8 pa0, bf16x8 pa1, bf16x8 pa2, bf16x8 pa3) {
;     const s16x4 l0 = tr_read<v_rd_off(D0, 0, 0)>(vb), h0 = tr_read<v_rd_off(D0, 0, 1)>(vb), l1 = tr_read<v_rd_off(D0, 1, 0)>(vb), h1 = tr_read<v_rd_off(D0, 1, 1)>(vb);
;     const s16x4 l2 = tr_read<v_rd_off(D0, 2, 0)>(vb), h2 = tr_read<v_rd_off(D0, 2, 1)>(vb), l3 = tr_read<v_rd_off(D0, 3, 0)>(vb), h3 = tr_read<v_rd_off(D0, 3, 1)>(vb);
;     asm volatile("s_waitcnt lgkmcnt(0)" ::: "memory"); SBAR();
;     ...
;     od = __builtin_amdgcn_mfma_f32_32x32x16_bf16(pa0, PK(l0, h0), od, 0, 0, 0);
;     od = __builtin_amdgcn_mfma_f32_32x32x16_bf16(pa1, PK(l1, h1), od, 0, 0, 0);
;     od = __builtin_amdgcn_mfma_f32_32x32x16_bf16(pa2, PK(l2, h2), od, 0, 0, 0);
;     od = __builtin_amdgcn_mfma_f32_32x32x16_bf16(pa3, PK(l3, h3), od, 0, 0, 0);
;     ...
; }
; template <bool RSM> __device__ __forceinline__ void pv_d0(f32x16* o, f32x16& lacc, int vb, bf16x8 pa0, bf16x8 pa1, bf16x8 pa2, bf16x8 pa3) {
;     if (RSM) {
;         const bf16x8 ones = {0x3F80, 0x3F80, 0x3F80, 0x3F80, 0x3F80, 0x3F80, 0x3F80, 0x3F80};
;         lacc = __builtin_amdgcn_mfma_f32_32x32x16_bf16(pa0, ones, lacc, 0, 0, 0);
;         lacc = __builtin_amdgcn_mfma_f32_32x32x16_bf16(pa1, ones, lacc, 0, 0, 0);
;         lacc = __builtin_amdgcn_mfma_f32_32x32x16_bf16(pa2, ones, lacc, 0, 0, 0);
;         lacc = __builtin_amdgcn_mfma_f32_32x32x16_bf16(pa3, ones, lacc, 0, 0, 0); }
;     pv_one<0>(o[0], vb, pa0, pa1, pa2, pa3); pv_one<1>(o[1], vb, pa0, pa1, pa2, pa3); pv_one<2>(o[2], vb, pa0, pa1, pa2, pa3); pv_one<3>(o[3], vb, pa0, pa1, pa2, pa3);
; }
	v_mfma_f32_32x32x16_bf16 v[48:63], v[6:9], v[148:151], v[48:63]
	ds_read_b64_tr_b16 v[148:149], v14 offset:0x600
	ds_read_b64_tr_b16 v[150:151], v14 offset:0xe00
	v_mfma_f32_32x32x16_bf16 v[48:63], v[2:5], v[152:155], v[48:63]
	ds_read_b64_tr_b16 v[152:153], v14 offset:0x1600
	ds_read_b64_tr_b16 v[154:155], v14 offset:0x1e00
	v_mfma_f32_32x32x16_bf16 v[48:63], v[144:147], v[156:159], v[48:63]
	ds_read_b64_tr_b16 v[156:157], v14 offset:0x2600
	ds_read_b64_tr_b16 v[158:159], v14 offset:0x2e00
	v_mfma_f32_32x32x16_bf16 v[48:63], v[10:13], v[192:195], v[48:63]
	ds_read_b64_tr_b16 v[192:193], v14 offset:0x3600
	ds_read_b64_tr_b16 v[194:195], v14 offset:0x3e00
	s_waitcnt lgkmcnt(0)
	v_mfma_f32_32x32x16_bf16 v[32:47], v[6:9], v[148:151], v[32:47]
	global_load_lds_dwordx4 v[214:215], off
	v_lshl_add_u64 v[214:215], v[214:215], 0, s[74:75]
	s_and_b64 vcc, exec, s[0:1]
	v_mfma_f32_32x32x16_bf16 v[32:47], v[2:5], v[152:155], v[32:47]
	s_mov_b32 m0, s22
	s_nop 0
	global_load_lds_dwordx4 v[212:213], off
	v_lshl_add_u64 v[212:213], v[212:213], 0, s[74:75]
	v_mfma_f32_32x32x16_bf16 v[32:47], v[144:147], v[156:159], v[32:47]
	s_add_i32 m0, s22, 0x2000
	s_nop 0
	global_load_lds_dwordx4 v[216:217], off
	v_lshl_add_u64 v[216:217], v[216:217], 0, s[74:75]
	v_mfma_f32_32x32x16_bf16 v[32:47], v[10:13], v[192:195], v[32:47]
	s_cbranch_vccnz .LBB0_724
	s_branch .Lmy_r2ft_1
.Lmy_r2d_2:
	s_mov_b32 s38, s36
	s_mov_b32 s39, s36
	s_mov_b32 s37, s36
	v_mov_b64_e32 v[118:119], s[38:39]
	v_mov_b64_e32 v[116:117], s[36:37]
	s_lshl_b32 s15, s18, 14
	v_add_u32_e32 v0, s15, v192
	v_mfma_f32_32x32x16_bf16 v[80:95], v[6:9], v[116:119], v[80:95]
	ds_read_b64_tr_b16 v[120:121], v0 offset:0
	ds_read_b64_tr_b16 v[122:123], v0 offset:0x800
	ds_read_b64_tr_b16 v[124:125], v0 offset:0x1000
	ds_read_b64_tr_b16 v[126:127], v0 offset:0x1800
	ds_read_b64_tr_b16 v[176:177], v0 offset:0x2000
	ds_read_b64_tr_b16 v[178:179], v0 offset:0x2800
	ds_read_b64_tr_b16 v[180:181], v0 offset:0x3000
	v_mfma_f32_32x32x16_bf16 v[80:95], v[2:5], v[116:119], v[80:95]
	ds_read_b64_tr_b16 v[182:183], v0 offset:0x3800
	s_waitcnt lgkmcnt(0)
	v_mfma_f32_32x32x16_bf16 v[80:95], v[112:115], v[116:119], v[80:95]
	v_mfma_f32_32x32x16_bf16 v[80:95], v[10:13], v[116:119], v[80:95]
	v_mfma_f32_32x32x16_bf16 v[64:79], v[6:9], v[120:123], v[64:79]
	ds_read_b64_tr_b16 v[116:117], v0 offset:0x200
	ds_read_b64_tr_b16 v[118:119], v0 offset:0xa00
	ds_read_b64_tr_b16 v[120:121], v0 offset:0x1200
	ds_read_b64_tr_b16 v[122:123], v0 offset:0x1a00
	v_mfma_f32_32x32x16_bf16 v[64:79], v[2:5], v[124:127], v[64:79]
	ds_read_b64_tr_b16 v[124:125], v0 offset:0x2200
	ds_read_b64_tr_b16 v[126:127], v0 offset:0x2a00
	v_mfma_f32_32x32x16_bf16 v[64:79], v[112:115], v[176:179], v[64:79]
	ds_read_b64_tr_b16 v[176:177], v0 offset:0x3200
	ds_read_b64_tr_b16 v[178:179], v0 offset:0x3a00
	s_waitcnt lgkmcnt(0)
	v_mfma_f32_32x32x16_bf16 v[64:79], v[10:13], v[180:183], v[64:79]
	v_mfma_f32_32x32x16_bf16 v[48:63], v[6:9], v[116:119], v[48:63]
	ds_read_b64_tr_b16 v[116:117], v0 offset:0x400
	ds_read_b64_tr_b16 v[118:119], v0 offset:0xc00
	v_mfma_f32_32x32x16_bf16 v[48:63], v[2:5], v[120:123], v[48:63]
	ds_read_b64_tr_b16 v[120:121], v0 offset:0x1400
	ds_read_b64_tr_b16 v[122:123], v0 offset:0x1c00
	v_mfma_f32_32x32x16_bf16 v[48:63], v[112:115], v[124:127], v[48:63]
	ds_read_b64_tr_b16 v[124:125], v0 offset:0x2400
	ds_read_b64_tr_b16 v[126:127], v0 offset:0x2c00
	v_mfma_f32_32x32x16_bf16 v[48:63], v[10:13], v[176:179], v[48:63]
	ds_read_b64_tr_b16 v[176:177], v0 offset:0x3400
	ds_read_b64_tr_b16 v[178:179], v0 offset:0x3c00
	s_waitcnt lgkmcnt(0)
	v_mfma_f32_32x32x16_bf16 v[32:47], v[6:9], v[116:119], v[32:47]
	ds_read_b64_tr_b16 v[116:117], v0 offset:0x600
	ds_read_b64_tr_b16 v[118:119], v0 offset:0xe00
	v_mfma_f32_32x32x16_bf16 v[32:47], v[2:5], v[120:123], v[32:47]
	ds_read_b64_tr_b16 v[120:121], v0 offset:0x1600
	ds_read_b64_tr_b16 v[122:123], v0 offset:0x1e00
	v_mfma_f32_32x32x16_bf16 v[32:47], v[112:115], v[124:127], v[32:47]
	ds_read_b64_tr_b16 v[124:125], v0 offset:0x2600
	ds_read_b64_tr_b16 v[126:127], v0 offset:0x2e00
	v_mfma_f32_32x32x16_bf16 v[32:47], v[10:13], v[176:179], v[32:47]
	ds_read_b64_tr_b16 v[176:177], v0 offset:0x3600
	ds_read_b64_tr_b16 v[178:179], v0 offset:0x3e00
	s_waitcnt lgkmcnt(0)
	v_mfma_f32_32x32x16_bf16 v[16:31], v[6:9], v[116:119], v[16:31]
	global_load_lds_dwordx4 v[184:185], off
	v_lshl_add_u64 v[184:185], v[184:185], 0, s[74:75]
	s_and_b64 vcc, exec, s[0:1]
	v_mfma_f32_32x32x16_bf16 v[16:31], v[2:5], v[120:123], v[16:31]
	s_mov_b32 m0, s12
	s_nop 0
	global_load_lds_dwordx4 v[186:187], off
	v_lshl_add_u64 v[186:187], v[186:187], 0, s[74:75]
	v_mfma_f32_32x32x16_bf16 v[16:31], v[112:115], v[124:127], v[16:31]
	s_add_i32 m0, s12, 0x2000
	s_nop 0
	global_load_lds_dwordx4 v[188:189], off
	v_lshl_add_u64 v[188:189], v[188:189], 0, s[74:75]
	v_mfma_f32_32x32x16_bf16 v[16:31], v[10:13], v[176:179], v[16:31]
	s_cbranch_vccnz .LBB0_784
	s_branch .Lmy_r2ft_2
; #define SBAR() __builtin_amdgcn_sched_barrier(0)
; template <int D0> __device__ __forceinline__ void pv_one(f32x16& od, int vb, bf16x8 pa0, bf16x8 pa1, bf16x8 pa2, bf16x8 pa3) {
;     const s16x4 l0 = tr_read<v_rd_off(D0, 0, 0)>(vb), h0 = tr_read<v_rd_off(D0, 0, 1)>(vb), l1 = tr_read<v_rd_off(D0, 1, 0)>(vb), h1 = tr_read<v_rd_off(D0, 1, 1)>(vb);
;     const s16x4 l2 = tr_read<v_rd_off(D0, 2, 0)>(vb), h2 = tr_read<v_rd_off(D0, 2, 1)>(vb), l3 = tr_read<v_rd_off(D0, 3, 0)>(vb), h3 = tr_read<v_rd_off(D0, 3, 1)>(vb);
;     asm volatile("s_waitcnt lgkmcnt(0)" ::: "memory"); SBAR();
;     ...
;     od = __builtin_amdgcn_mfma_f32_32x32x16_bf16(pa0, PK(l0, h0), od, 0, 0, 0);
;     od = __builtin_amdgcn_mfma_f32_32x32x16_bf16(pa1, PK(l1, h1), od, 0, 0, 0);
;     od = __builtin_amdgcn_mfma_f32_32x32x16_bf16(pa2, PK(l2, h2), od, 0, 0, 0);
;     od = __builtin_amdgcn_mfma_f32_32x32x16_bf16(pa3, PK(l3, h3), od, 0, 0, 0);
;     ...
; }
; template <bool RSM> __device__ __forceinline__ void pv_d0(f32x16* o, f32x16& lacc, int vb, bf16x8 pa0, bf16x8 pa1, bf16x8 pa2, bf16x8 pa3) {
;     if (RSM) {
;         const bf16x8 ones = {0x3F80, 0x3F80, 0x3F80, 0x3F80, 0x3F80, 0x3F80, 0x3F80, 0x3F80};
;         lacc = __builtin_amdgcn_mfma_f32_32x32x16_bf16(pa0, ones, lacc, 0, 0, 0);
;         lacc = __builtin_amdgcn_mfma_f32_32x32x16_bf16(pa1, ones, lacc, 0, 0, 0);
;         lacc = __builtin_amdgcn_mfma_f32_32x32x16_bf16(pa2, ones, lacc, 0, 0, 0);
;         lacc = __builtin_amdgcn_mfma_f32_32x32x16_bf16(pa3, ones, lacc, 0, 0, 0); }
;     pv_one<0>(o[0], vb, pa0, pa1, pa2, pa3); pv_one<1>(o[1], vb, pa0, pa1, pa2, pa3); pv_one<2>(o[2], vb, pa0, pa1, pa2, pa3); pv_one<3>(o[3], vb, pa0, pa1, pa2, pa3);
; }
.Lmy_r2d_3:
	s_mov_b32 s38, s36
	s_mov_b32 s39, s36
	s_mov_b32 s37, s36
	v_mov_b64_e32 v[134:135], s[38:39]
	v_mov_b64_e32 v[132:133], s[36:37]
	s_lshl_b32 s31, s18, 14
	v_add_u32_e32 v14, s31, v192
	v_mfma_f32_32x32x16_bf16 v[80:95], v[6:9], v[132:135], v[80:95]
	ds_read_b64_tr_b16 v[136:137], v14 offset:0
	ds_read_b64_tr_b16 v[138:139], v14 offset:0x800
	ds_read_b64_tr_b16 v[140:141], v14 offset:0x1000
	ds_read_b64_tr_b16 v[142:143], v14 offset:0x1800
	ds_read_b64_tr_b16 v[176:177], v14 offset:0x2000
	ds_read_b64_tr_b16 v[178:179], v14 offset:0x2800
	ds_read_b64_tr_b16 v[180:181], v14 offset:0x3000
	v_mfma_f32_32x32x16_bf16 v[80:95], v[2:5], v[132:135], v[80:95]
	ds_read_b64_tr_b16 v[182:183], v14 offset:0x3800
	s_waitcnt lgkmcnt(0)
	v_mfma_f32_32x32x16_bf16 v[80:95], v[128:131], v[132:135], v[80:95]
	v_mfma_f32_32x32x16_bf16 v[80:95], v[10:13], v[132:135], v[80:95]
	v_mfma_f32_32x32x16_bf16 v[64:79], v[6:9], v[136:139], v[64:79]
	ds_read_b64_tr_b16 v[132:133], v14 offset:0x200
	ds_read_b64_tr_b16 v[134:135], v14 offset:0xa00
	ds_read_b64_tr_b16 v[136:137], v14 offset:0x1200
	ds_read_b64_tr_b16 v[138:139], v14 offset:0x1a00
	v_mfma_f32_32x32x16_bf16 v[64:79], v[2:5], v[140:143], v[64:79]
	ds_read_b64_tr_b16 v[140:141], v14 offset:0x2200
	ds_read_b64_tr_b16 v[142:143], v14 offset:0x2a00
	v_mfma_f32_32x32x16_bf16 v[64:79], v[128:131], v[176:179], v[64:79]
	ds_read_b64_tr_b16 v[176:177], v14 offset:0x3200
	ds_read_b64_tr_b16 v[178:179], v14 offset:0x3a00
	s_waitcnt lgkmcnt(0)
	v_mfma_f32_32x32x16_bf16 v[64:79], v[10:13], v[180:183], v[64:79]
	v_mfma_f32_32x32x16_bf16 v[48:63], v[6:9], v[132:135], v[48:63]
	ds_read_b64_tr_b16 v[132:133], v14 offset:0x400
	ds_read_b64_tr_b16 v[134:135], v14 offset:0xc00
	v_mfma_f32_32x32x16_bf16 v[48:63], v[2:5], v[136:139], v[48:63]
	ds_read_b64_tr_b16 v[136:137], v14 offset:0x1400
	ds_read_b64_tr_b16 v[138:139], v14 offset:0x1c00
	v_mfma_f32_32x32x16_bf16 v[48:63], v[128:131], v[140:143], v[48:63]
	ds_read_b64_tr_b16 v[140:141], v14 offset:0x2400
	ds_read_b64_tr_b16 v[142:143], v14 offset:0x2c00
	v_mfma_f32_32x32x16_bf16 v[48:63], v[10:13], v[176:179], v[48:63]
	ds_read_b64_tr_b16 v[176:177], v14 offset:0x3400
	ds_read_b64_tr_b16 v[178:179], v14 offset:0x3c00
	s_waitcnt lgkmcnt(0)
	v_mfma_f32_32x32x16_bf16 v[32:47], v[6:9], v[132:135], v[32:47]
	ds_read_b64_tr_b16 v[132:133], v14 offset:0x600
	ds_read_b64_tr_b16 v[134:135], v14 offset:0xe00
	v_mfma_f32_32x32x16_bf16 v[32:47], v[2:5], v[136:139], v[32:47]
	ds_read_b64_tr_b16 v[136:137], v14 offset:0x1600
	ds_read_b64_tr_b16 v[138:139], v14 offset:0x1e00
	v_mfma_f32_32x32x16_bf16 v[32:47], v[128:131], v[140:143], v[32:47]
	ds_read_b64_tr_b16 v[140:141], v14 offset:0x2600
	ds_read_b64_tr_b16 v[142:143], v14 offset:0x2e00
	v_mfma_f32_32x32x16_bf16 v[32:47], v[10:13], v[176:179], v[32:47]
	ds_read_b64_tr_b16 v[176:177], v14 offset:0x3600
	ds_read_b64_tr_b16 v[178:179], v14 offset:0x3e00
	s_waitcnt lgkmcnt(0)
	v_mfma_f32_32x32x16_bf16 v[16:31], v[6:9], v[132:135], v[16:31]
	global_load_lds_dwordx4 v[184:185], off
	v_lshl_add_u64 v[184:185], v[184:185], 0, s[74:75]
	s_and_b64 vcc, exec, s[0:1]
	v_mfma_f32_32x32x16_bf16 v[16:31], v[2:5], v[136:139], v[16:31]
	s_mov_b32 m0, s14
	s_nop 0
	global_load_lds_dwordx4 v[186:187], off
	v_lshl_add_u64 v[186:187], v[186:187], 0, s[74:75]
	v_mfma_f32_32x32x16_bf16 v[16:31], v[128:131], v[140:143], v[16:31]
	s_add_i32 m0, s14, 0x2000
	s_nop 0
	global_load_lds_dwordx4 v[188:189], off
	v_lshl_add_u64 v[188:189], v[188:189], 0, s[74:75]
	v_mfma_f32_32x32x16_bf16 v[16:31], v[10:13], v[176:179], v[16:31]
	s_cbranch_vccnz .LBB0_799
	s_branch .Lmy_r2ft_3

; #define SBAR() __builtin_amdgcn_sched_barrier(0)
; template <int D0> __device__ __forceinline__ void pv_one(f32x16& od, int vb, bf16x8 pa0, bf16x8 pa1, bf16x8 pa2, bf16x8 pa3) {
;     const s16x4 l0 = tr_read<v_rd_off(D0, 0, 0)>(vb), h0 = tr_read<v_rd_off(D0, 0, 1)>(vb), l1 = tr_read<v_rd_off(D0, 1, 0)>(vb), h1 = tr_read<v_rd_off(D0, 1, 1)>(vb);
;     const s16x4 l2 = tr_read<v_rd_off(D0, 2, 0)>(vb), h2 = tr_read<v_rd_off(D0, 2, 1)>(vb), l3 = tr_read<v_rd_off(D0, 3, 0)>(vb), h3 = tr_read<v_rd_off(D0, 3, 1)>(vb);
;     asm volatile("s_waitcnt lgkmcnt(0)" ::: "memory"); SBAR();
;     ...
;     od = __builtin_amdgcn_mfma_f32_32x32x16_bf16(pa0, PK(l0, h0), od, 0, 0, 0);
;     od = __builtin_amdgcn_mfma_f32_32x32x16_bf16(pa1, PK(l1, h1), od, 0, 0, 0);
;     od = __builtin_amdgcn_mfma_f32_32x32x16_bf16(pa2, PK(l2, h2), od, 0, 0, 0);
;     od = __builtin_amdgcn_mfma_f32_32x32x16_bf16(pa3, PK(l3, h3), od, 0, 0, 0);
;     ...
; }
; template <bool RSM> __device__ __forceinline__ void pv_d0(f32x16* o, f32x16& lacc, int vb, bf16x8 pa0, bf16x8 pa1, bf16x8 pa2, bf16x8 pa3) {
;     if (RSM) {
;         const bf16x8 ones = {0x3F80, 0x3F80, 0x3F80, 0x3F80, 0x3F80, 0x3F80, 0x3F80, 0x3F80};
;         lacc = __builtin_amdgcn_mfma_f32_32x32x16_bf16(pa0, ones, lacc, 0, 0, 0);
;         lacc = __builtin_amdgcn_mfma_f32_32x32x16_bf16(pa1, ones, lacc, 0, 0, 0);
;         lacc = __builtin_amdgcn_mfma_f32_32x32x16_bf16(pa2, ones, lacc, 0, 0, 0);
;         lacc = __builtin_amdgcn_mfma_f32_32x32x16_bf16(pa3, ones, lacc, 0, 0, 0); }
;     pv_one<0>(o[0], vb, pa0, pa1, pa2, pa3); pv_one<1>(o[1], vb, pa0, pa1, pa2, pa3); pv_one<2>(o[2], vb, pa0, pa1, pa2, pa3); pv_one<3>(o[3], vb, pa0, pa1, pa2, pa3);
; }
.LBB0_779:
	s_mov_b32 s38, s36
	s_mov_b32 s39, s36
	s_mov_b32 s37, s36
	v_mov_b64_e32 v[118:119], s[38:39]
	v_mov_b64_e32 v[116:117], s[36:37]
	s_lshl_b32 s15, s18, 14
	v_add_u32_e32 v0, s15, v192
	v_mfma_f32_32x32x16_bf16 v[80:95], v[6:9], v[116:119], v[80:95]
	ds_read_b64_tr_b16 v[120:121], v0 offset:0
	ds_read_b64_tr_b16 v[122:123], v0 offset:0x800
	ds_read_b64_tr_b16 v[124:125], v0 offset:0x1000
	ds_read_b64_tr_b16 v[126:127], v0 offset:0x1800
	ds_read_b64_tr_b16 v[176:177], v0 offset:0x2000
	ds_read_b64_tr_b16 v[178:179], v0 offset:0x2800
	ds_read_b64_tr_b16 v[180:181], v0 offset:0x3000
	v_mfma_f32_32x32x16_bf16 v[80:95], v[2:5], v[116:119], v[80:95]
	ds_read_b64_tr_b16 v[182:183], v0 offset:0x3800
	s_waitcnt lgkmcnt(0)
	v_mfma_f32_32x32x16_bf16 v[80:95], v[112:115], v[116:119], v[80:95]
	v_mfma_f32_32x32x16_bf16 v[80:95], v[10:13], v[116:119], v[80:95]
	v_mfma_f32_32x32x16_bf16 v[64:79], v[6:9], v[120:123], v[64:79]
	ds_read_b64_tr_b16 v[116:117], v0 offset:0x200
	ds_read_b64_tr_b16 v[118:119], v0 offset:0xa00
	ds_read_b64_tr_b16 v[120:121], v0 offset:0x1200
	ds_read_b64_tr_b16 v[122:123], v0 offset:0x1a00
	v_mfma_f32_32x32x16_bf16 v[64:79], v[2:5], v[124:127], v[64:79]
	ds_read_b64_tr_b16 v[124:125], v0 offset:0x2200
	ds_read_b64_tr_b16 v[126:127], v0 offset:0x2a00
	v_mfma_f32_32x32x16_bf16 v[64:79], v[112:115], v[176:179], v[64:79]
	ds_read_b64_tr_b16 v[176:177], v0 offset:0x3200
	ds_read_b64_tr_b16 v[178:179], v0 offset:0x3a00
	s_waitcnt lgkmcnt(0)
	v_mfma_f32_32x32x16_bf16 v[64:79], v[10:13], v[180:183], v[64:79]
	v_mfma_f32_32x32x16_bf16 v[48:63], v[6:9], v[116:119], v[48:63]
	ds_read_b64_tr_b16 v[116:117], v0 offset:0x400
	ds_read_b64_tr_b16 v[118:119], v0 offset:0xc00
	v_mfma_f32_32x32x16_bf16 v[48:63], v[2:5], v[120:123], v[48:63]
	ds_read_b64_tr_b16 v[120:121], v0 offset:0x1400
	ds_read_b64_tr_b16 v[122:123], v0 offset:0x1c00
	v_mfma_f32_32x32x16_bf16 v[48:63], v[112:115], v[124:127], v[48:63]
	ds_read_b64_tr_b16 v[124:125], v0 offset:0x2400
	ds_read_b64_tr_b16 v[126:127], v0 offset:0x2c00
	v_mfma_f32_32x32x16_bf16 v[48:63], v[10:13], v[176:179], v[48:63]
	ds_read_b64_tr_b16 v[176:177], v0 offset:0x3400
	ds_read_b64_tr_b16 v[178:179], v0 offset:0x3c00
	s_waitcnt lgkmcnt(0)
	v_mfma_f32_32x32x16_bf16 v[32:47], v[6:9], v[116:119], v[32:47]
	ds_read_b64_tr_b16 v[116:117], v0 offset:0x600
	ds_read_b64_tr_b16 v[118:119], v0 offset:0xe00
	v_mfma_f32_32x32x16_bf16 v[32:47], v[2:5], v[120:123], v[32:47]
	ds_read_b64_tr_b16 v[120:121], v0 offset:0x1600
	ds_read_b64_tr_b16 v[122:123], v0 offset:0x1e00
	v_mfma_f32_32x32x16_bf16 v[32:47], v[112:115], v[124:127], v[32:47]
	ds_read_b64_tr_b16 v[124:125], v0 offset:0x2600
	ds_read_b64_tr_b16 v[126:127], v0 offset:0x2e00
	v_mfma_f32_32x32x16_bf16 v[32:47], v[10:13], v[176:179], v[32:47]
	ds_read_b64_tr_b16 v[176:177], v0 offset:0x3600
	ds_read_b64_tr_b16 v[178:179], v0 offset:0x3e00
	s_waitcnt lgkmcnt(0)
	s_and_b64 vcc, exec, s[0:1]
	s_cbranch_vccnz .Lmy_slow_2
	s_cmpk_gt_u32 s17, 0xfc
	s_cbranch_scc1 .Lmy_slow_2
	s_mov_b64 s[12:13], -1
	s_add_i32 m0, s81, s14
	s_addk_i32 s15, 0xc000
	s_cmp_gt_i32 s18, 0
	s_cselect_b32 s12, s15, 0xc000
	s_waitcnt vmcnt(3) lgkmcnt(0)
	s_barrier
	v_mfma_f32_32x32x16_bf16 v[16:31], v[6:9], v[116:119], v[16:31]
	global_load_lds_dwordx4 v[184:185], off
	v_lshl_add_u64 v[184:185], v[184:185], 0, s[74:75]
	s_and_b64 vcc, exec, s[0:1]
	v_mfma_f32_32x32x16_bf16 v[16:31], v[2:5], v[120:123], v[16:31]
	s_add_i32 s12, s63, s12
	s_mov_b32 m0, s12
	s_nop 0
	global_load_lds_dwordx4 v[186:187], off
	v_mfma_f32_32x32x16_bf16 v[16:31], v[112:115], v[124:127], v[16:31]
	s_add_i32 m0, s12, 0x2000
	s_nop 0
	global_load_lds_dwordx4 v[188:189], off
	v_mfma_f32_32x32x16_bf16 v[16:31], v[10:13], v[176:179], v[16:31]
	v_lshl_add_u64 v[2:3], v[186:187], 0, s[74:75]
	v_lshl_add_u64 v[4:5], v[188:189], 0, s[74:75]
	v_mov_b64_e32 v[188:189], v[4:5]
	v_mov_b64_e32 v[186:187], v[2:3]
	s_branch .LBB0_784

; #define SBAR() __builtin_amdgcn_sched_barrier(0)
; template <int D0> __device__ __forceinline__ void pv_one(f32x16& od, int vb, bf16x8 pa0, bf16x8 pa1, bf16x8 pa2, bf16x8 pa3) {
;     const s16x4 l0 = tr_read<v_rd_off(D0, 0, 0)>(vb), h0 = tr_read<v_rd_off(D0, 0, 1)>(vb), l1 = tr_read<v_rd_off(D0, 1, 0)>(vb), h1 = tr_read<v_rd_off(D0, 1, 1)>(vb);
;     const s16x4 l2 = tr_read<v_rd_off(D0, 2, 0)>(vb), h2 = tr_read<v_rd_off(D0, 2, 1)>(vb), l3 = tr_read<v_rd_off(D0, 3, 0)>(vb), h3 = tr_read<v_rd_off(D0, 3, 1)>(vb);
;     asm volatile("s_waitcnt lgkmcnt(0)" ::: "memory"); SBAR();
;     ...
;     od = __builtin_amdgcn_mfma_f32_32x32x16_bf16(pa0, PK(l0, h0), od, 0, 0, 0);
;     od = __builtin_amdgcn_mfma_f32_32x32x16_bf16(pa1, PK(l1, h1), od, 0, 0, 0);
;     od = __builtin_amdgcn_mfma_f32_32x32x16_bf16(pa2, PK(l2, h2), od, 0, 0, 0);
;     od = __builtin_amdgcn_mfma_f32_32x32x16_bf16(pa3, PK(l3, h3), od, 0, 0, 0);
;     ...
; }
; template <bool RSM> __device__ __forceinline__ void pv_d0(f32x16* o, f32x16& lacc, int vb, bf16x8 pa0, bf16x8 pa1, bf16x8 pa2, bf16x8 pa3) {
;     if (RSM) {
;         const bf16x8 ones = {0x3F80, 0x3F80, 0x3F80, 0x3F80, 0x3F80, 0x3F80, 0x3F80, 0x3F80};
;         lacc = __builtin_amdgcn_mfma_f32_32x32x16_bf16(pa0, ones, lacc, 0, 0, 0);
;         lacc = __builtin_amdgcn_mfma_f32_32x32x16_bf16(pa1, ones, lacc, 0, 0, 0);
;         lacc = __builtin_amdgcn_mfma_f32_32x32x16_bf16(pa2, ones, lacc, 0, 0, 0);
;         lacc = __builtin_amdgcn_mfma_f32_32x32x16_bf16(pa3, ones, lacc, 0, 0, 0); }
;     pv_one<0>(o[0], vb, pa0, pa1, pa2, pa3); pv_one<1>(o[1], vb, pa0, pa1, pa2, pa3); pv_one<2>(o[2], vb, pa0, pa1, pa2, pa3); pv_one<3>(o[3], vb, pa0, pa1, pa2, pa3);
; }
.LBB0_794:
	s_mov_b32 s38, s36
	s_mov_b32 s39, s36
	s_mov_b32 s37, s36
	v_mov_b64_e32 v[134:135], s[38:39]
	v_mov_b64_e32 v[132:133], s[36:37]
	s_lshl_b32 s31, s18, 14
	v_add_u32_e32 v14, s31, v192
	v_mfma_f32_32x32x16_bf16 v[80:95], v[6:9], v[132:135], v[80:95]
	ds_read_b64_tr_b16 v[136:137], v14 offset:0
	ds_read_b64_tr_b16 v[138:139], v14 offset:0x800
	ds_read_b64_tr_b16 v[140:141], v14 offset:0x1000
	ds_read_b64_tr_b16 v[142:143], v14 offset:0x1800
	ds_read_b64_tr_b16 v[176:177], v14 offset:0x2000
	ds_read_b64_tr_b16 v[178:179], v14 offset:0x2800
	ds_read_b64_tr_b16 v[180:181], v14 offset:0x3000
	v_mfma_f32_32x32x16_bf16 v[80:95], v[2:5], v[132:135], v[80:95]
	ds_read_b64_tr_b16 v[182:183], v14 offset:0x3800
	s_waitcnt lgkmcnt(0)
	v_mfma_f32_32x32x16_bf16 v[80:95], v[128:131], v[132:135], v[80:95]
	v_mfma_f32_32x32x16_bf16 v[80:95], v[10:13], v[132:135], v[80:95]
	v_mfma_f32_32x32x16_bf16 v[64:79], v[6:9], v[136:139], v[64:79]
	ds_read_b64_tr_b16 v[132:133], v14 offset:0x200
	ds_read_b64_tr_b16 v[134:135], v14 offset:0xa00
	ds_read_b64_tr_b16 v[136:137], v14 offset:0x1200
	ds_read_b64_tr_b16 v[138:139], v14 offset:0x1a00
	v_mfma_f32_32x32x16_bf16 v[64:79], v[2:5], v[140:143], v[64:79]
	ds_read_b64_tr_b16 v[140:141], v14 offset:0x2200
	ds_read_b64_tr_b16 v[142:143], v14 offset:0x2a00
	v_mfma_f32_32x32x16_bf16 v[64:79], v[128:131], v[176:179], v[64:79]
	ds_read_b64_tr_b16 v[176:177], v14 offset:0x3200
	ds_read_b64_tr_b16 v[178:179], v14 offset:0x3a00
	s_waitcnt lgkmcnt(0)
	v_mfma_f32_32x32x16_bf16 v[64:79], v[10:13], v[180:183], v[64:79]
	v_mfma_f32_32x32x16_bf16 v[48:63], v[6:9], v[132:135], v[48:63]
	ds_read_b64_tr_b16 v[132:133], v14 offset:0x400
	ds_read_b64_tr_b16 v[134:135], v14 offset:0xc00
	v_mfma_f32_32x32x16_bf16 v[48:63], v[2:5], v[136:139], v[48:63]
	ds_read_b64_tr_b16 v[136:137], v14 offset:0x1400
	ds_read_b64_tr_b16 v[138:139], v14 offset:0x1c00
	v_mfma_f32_32x32x16_bf16 v[48:63], v[128:131], v[140:143], v[48:63]
	ds_read_b64_tr_b16 v[140:141], v14 offset:0x2400
	ds_read_b64_tr_b16 v[142:143], v14 offset:0x2c00
	v_mfma_f32_32x32x16_bf16 v[48:63], v[10:13], v[176:179], v[48:63]
	ds_read_b64_tr_b16 v[176:177], v14 offset:0x3400
	ds_read_b64_tr_b16 v[178:179], v14 offset:0x3c00
	s_waitcnt lgkmcnt(0)
	v_mfma_f32_32x32x16_bf16 v[32:47], v[6:9], v[132:135], v[32:47]
	ds_read_b64_tr_b16 v[132:133], v14 offset:0x600
	ds_read_b64_tr_b16 v[134:135], v14 offset:0xe00
	v_mfma_f32_32x32x16_bf16 v[32:47], v[2:5], v[136:139], v[32:47]
	ds_read_b64_tr_b16 v[136:137], v14 offset:0x1600
	ds_read_b64_tr_b16 v[138:139], v14 offset:0x1e00
	v_mfma_f32_32x32x16_bf16 v[32:47], v[128:131], v[140:143], v[32:47]
	ds_read_b64_tr_b16 v[140:141], v14 offset:0x2600
	ds_read_b64_tr_b16 v[142:143], v14 offset:0x2e00
	v_mfma_f32_32x32x16_bf16 v[32:47], v[10:13], v[176:179], v[32:47]
	ds_read_b64_tr_b16 v[176:177], v14 offset:0x3600
	ds_read_b64_tr_b16 v[178:179], v14 offset:0x3e00
	s_waitcnt lgkmcnt(0)
	s_and_b64 vcc, exec, s[0:1]
	s_cbranch_vccnz .Lmy_slow_3
	s_cmpk_gt_u32 s17, 0xfb
	s_cbranch_scc1 .Lmy_slow_3
	s_mov_b64 s[14:15], -1
	s_add_i32 m0, s81, s26
	s_addk_i32 s31, 0xc000
	s_cmp_gt_i32 s18, 0
	s_cselect_b32 s14, s31, 0xc000
	s_waitcnt vmcnt(3) lgkmcnt(0)
	s_barrier
	v_mfma_f32_32x32x16_bf16 v[16:31], v[6:9], v[132:135], v[16:31]
	global_load_lds_dwordx4 v[184:185], off
	v_lshl_add_u64 v[184:185], v[184:185], 0, s[74:75]
	s_and_b64 vcc, exec, s[0:1]
	v_mfma_f32_32x32x16_bf16 v[16:31], v[2:5], v[136:139], v[16:31]
	s_add_i32 s14, s63, s14
	s_mov_b32 m0, s14
	s_nop 0
	global_load_lds_dwordx4 v[186:187], off
	v_mfma_f32_32x32x16_bf16 v[16:31], v[128:131], v[140:143], v[16:31]
	s_add_i32 m0, s14, 0x2000
	s_nop 0
	global_load_lds_dwordx4 v[188:189], off
	v_mfma_f32_32x32x16_bf16 v[16:31], v[10:13], v[176:179], v[16:31]
	v_lshl_add_u64 v[2:3], v[186:187], 0, s[74:75]
	v_lshl_add_u64 v[4:5], v[188:189], 0, s[74:75]
	v_mov_b64_e32 v[188:189], v[4:5]
	v_mov_b64_e32 v[186:187], v[2:3]
	s_branch .LBB0_799
